# P0 rmsnorm row loop: the 8 loop-invariant norm-weight loads hoisted out of the loop, per-piece vmcnt(0) drains removed (on top of v13)
# speedup vs baseline: 1.0038x; 1.0038x over previous
; __device__ __forceinline__ void rms_rows_bf16(const float* srcA, const float* srcB, const float* w, bf16_t* dst, int gw, int NGW, int lane) {
;     for (int m = gw; m < MROWS; m += NGW) {
;         const float* src = (m < SEQ_P) ? srcA + (size_t)m * DM : srcB + (size_t)(m - SEQ_P) * DM;
;         f32x4 v[8]; float s = 0.f;
; #pragma unroll
;         for (int j = 0; j < 8; ++j) { v[j] = ((const f32x4*)src)[lane + 64 * j]; s += (v[j].x * v[j].x + v[j].y * v[j].y) + (v[j].z * v[j].z + v[j].w * v[j].w); }
;         const float rs = rsqrtf(wave_sum(s) * (1.f / DM) + EPS);
; #pragma unroll
;         for (int j = 0; j < 8; ++j) { const f32x4 wv = ((const f32x4*)w)[lane + 64 * j]; const f32x4 o = v[j] * rs * wv;
;             u32x2 p; p.x = pk2(o.x, o.y); p.y = pk2(o.z, o.w); ((u32x2*)(dst + (size_t)m * DM))[lane + 64 * j] = p; }
.LBB0_43:
	s_or_b64 exec, exec, s[8:9]
	s_add_i32 s2, 0, 0x23004
	v_mov_b32_e32 v1, s2
	s_add_i32 s2, 0, 0x23000
	ds_read_b32 v1, v1
	v_mov_b32_e32 v2, s2
	s_add_i32 s2, 0, 0x2300c
	ds_read_b32 v2, v2
	v_mov_b32_e32 v3, s2
	ds_read_b32 v3, v3
	s_add_i32 s7, 0, 0x23008
	s_waitcnt lgkmcnt(2)
	v_readfirstlane_b32 s8, v1
	v_mov_b32_e32 v1, s7
	s_add_i32 s7, 0, 0x23014
	s_waitcnt lgkmcnt(1)
	v_readfirstlane_b32 s14, v2
	v_mov_b32_e32 v2, s7
	s_add_i32 s7, 0, 0x23010
	s_waitcnt lgkmcnt(0)
	v_readfirstlane_b32 s2, v3
	v_mov_b32_e32 v3, s7
	s_add_i32 s7, 0, 0x230ec
	v_mov_b32_e32 v4, s7
	s_add_i32 s7, 0, 0x230e8
	v_mov_b32_e32 v5, s7
	ds_read_b32 v1, v1
	ds_read_b32 v2, v2
	ds_read_b32 v3, v3
	ds_read_b32 v4, v4
	ds_read_b32 v5, v5
	s_mov_b32 s9, 0
	s_waitcnt lgkmcnt(4)
	v_readfirstlane_b32 s18, v1
	s_waitcnt lgkmcnt(3)
	v_readfirstlane_b32 s13, v2
	s_waitcnt lgkmcnt(2)
	v_readfirstlane_b32 s12, v3
	s_waitcnt lgkmcnt(1)
	v_readfirstlane_b32 s11, v4
	s_waitcnt lgkmcnt(0)
	v_readfirstlane_b32 s10, v5
	s_cmpk_gt_i32 s6, 0x5fff
	v_mbcnt_lo_u32_b32 v167, -1, 0
	s_cbranch_scc1 .LBB0_48
	v_mbcnt_hi_u32_b32 v2, -1, v167
	v_and_b32_e32 v1, 64, v2
	v_add_u32_e32 v3, 64, v1
	v_xor_b32_e32 v1, 1, v2
	v_cmp_lt_i32_e32 vcc, v1, v3
	v_xor_b32_e32 v4, 2, v2
	v_or_b32_e32 v8, 0x140, v6
	v_cndmask_b32_e32 v1, v2, v1, vcc
	v_cmp_lt_i32_e32 vcc, v4, v3
	v_or_b32_e32 v10, 0x180, v6
	v_or_b32_e32 v12, 0x1c0, v6
	v_cndmask_b32_e32 v4, v2, v4, vcc
	v_lshlrev_b32_e32 v42, 2, v4
	v_xor_b32_e32 v4, 4, v2
	v_cmp_lt_i32_e32 vcc, v4, v3
	s_ashr_i32 s7, s6, 31
	s_ashr_i32 s73, s72, 31
	v_cndmask_b32_e32 v4, v2, v4, vcc
	v_lshlrev_b32_e32 v43, 2, v4
	v_xor_b32_e32 v4, 8, v2
	v_cmp_lt_i32_e32 vcc, v4, v3
	v_lshlrev_b32_e32 v1, 2, v1
	v_lshlrev_b32_e32 v47, 4, v6
	v_cndmask_b32_e32 v4, v2, v4, vcc
	v_lshlrev_b32_e32 v44, 2, v4
	v_xor_b32_e32 v4, 16, v2
	v_cmp_lt_i32_e32 vcc, v4, v3
	v_lshlrev_b32_e32 v49, 4, v8
	v_lshlrev_b32_e32 v50, 4, v10
	v_cndmask_b32_e32 v4, v2, v4, vcc
	v_lshlrev_b32_e32 v45, 2, v4
	v_xor_b32_e32 v4, 32, v2
	v_cmp_lt_i32_e32 vcc, v4, v3
	v_mov_b32_e32 v3, 0
	v_lshlrev_b32_e32 v51, 4, v12
	v_cndmask_b32_e32 v2, v2, v4, vcc
	v_lshlrev_b32_e32 v46, 2, v2
	v_lshlrev_b32_e32 v2, 4, v6
	v_or_b32_e32 v4, 0x100, v6
	v_lshl_add_u64 v[30:31], s[12:13], 0, v[2:3]
	v_lshlrev_b32_e32 v2, 4, v4
	v_lshl_add_u64 v[32:33], s[12:13], 0, v[2:3]
	v_lshlrev_b32_e32 v2, 4, v8
	v_lshl_add_u64 v[34:35], s[12:13], 0, v[2:3]
	v_lshlrev_b32_e32 v2, 4, v10
	v_lshl_add_u64 v[36:37], s[12:13], 0, v[2:3]
	v_lshlrev_b32_e32 v2, 4, v12
	v_lshl_add_u64 v[38:39], s[12:13], 0, v[2:3]
	v_lshlrev_b32_e32 v2, 3, v6
	v_lshl_add_u64 v[2:3], s[10:11], 0, v[2:3]
	s_mov_b64 s[10:11], 0x2200000
	v_lshl_add_u64 v[40:41], v[2:3], 0, s[10:11]
	s_lshl_b64 s[10:11], s[6:7], 13
	s_add_u32 s10, s14, s10
	s_addc_u32 s11, s8, s11
	s_lshl_b64 s[12:13], s[72:73], 13
	v_lshlrev_b32_e32 v48, 4, v4
	v_mov_b32_e32 v52, 0x358637bd
	s_mov_b32 s19, 0x800000
	s_mov_b32 s22, 0x7060302
	global_load_dwordx4 v[100:103], v[30:31], off
	global_load_dwordx4 v[104:107], v[30:31], off offset:1024
	global_load_dwordx4 v[108:111], v[30:31], off offset:2048
	global_load_dwordx4 v[112:115], v[30:31], off offset:3072
	global_load_dwordx4 v[116:119], v[32:33], off
	global_load_dwordx4 v[120:123], v[34:35], off
	global_load_dwordx4 v[124:127], v[36:37], off
	global_load_dwordx4 v[128:131], v[38:39], off
	s_branch .LBB0_46
.LBB0_45:
	global_load_dwordx4 v[26:29], v47, s[16:17]
	global_load_dwordx4 v[14:17], v47, s[16:17] offset:1024
	global_load_dwordx4 v[18:21], v47, s[16:17] offset:2048
	global_load_dwordx4 v[10:13], v49, s[16:17]
	global_load_dwordx4 v[22:25], v48, s[16:17]
	global_load_dwordx4 v[54:57], v47, s[16:17] offset:3072
	global_load_dwordx4 v[6:9], v50, s[16:17]
	global_load_dwordx4 v[2:5], v51, s[16:17]
	s_lshl_b64 s[14:15], s[14:15], 12
	s_add_u32 s6, s6, s72
	s_addc_u32 s7, s7, s73
	s_add_u32 s10, s10, s12
	s_addc_u32 s11, s11, s13
	s_cmpk_gt_i32 s6, 0x5fff
	s_waitcnt vmcnt(7)
	v_mov_b32_e32 v64, v27
	s_waitcnt vmcnt(6)
	v_mov_b32_e32 v65, v15
	s_waitcnt vmcnt(5)
	v_pk_mul_f32 v[68:69], v[20:21], v[20:21]
	v_pk_mul_f32 v[70:71], v[18:19], v[18:19]
	s_waitcnt vmcnt(4)
	v_pk_mul_f32 v[72:73], v[12:13], v[12:13]
	v_pk_mul_f32 v[74:75], v[10:11], v[10:11]
	v_mov_b32_e32 v76, v29
	v_mov_b32_e32 v77, v17
	v_mov_b32_e32 v62, v26
	v_mov_b32_e32 v63, v14
	v_mov_b32_e32 v66, v28
	v_mov_b32_e32 v67, v16
	v_pk_mov_b32 v[86:87], v[70:71], v[68:69] op_sel:[1,0]
	v_mov_b32_e32 v71, v69
	v_pk_mov_b32 v[68:69], v[74:75], v[72:73] op_sel:[1,0]
	v_mov_b32_e32 v75, v73
	v_pk_mul_f32 v[64:65], v[64:65], v[64:65]
	v_pk_mul_f32 v[72:73], v[76:77], v[76:77]
	v_pk_fma_f32 v[62:63], v[62:63], v[62:63], v[64:65]
	v_pk_fma_f32 v[64:65], v[66:67], v[66:67], v[72:73]
	s_waitcnt vmcnt(2)
	v_mul_f32_e32 v78, v55, v55
	v_mul_f32_e32 v80, v57, v57
	v_pk_add_f32 v[66:67], v[86:87], v[70:71]
	v_pk_add_f32 v[62:63], v[62:63], v[64:65]
	v_mul_f32_e32 v53, v24, v24
	v_mul_f32_e32 v85, v25, v25
	v_mul_f32_e32 v90, v22, v22
	v_mul_f32_e32 v91, v23, v23
	v_pk_fma_f32 v[76:77], v[54:55], v[54:55], v[78:79] op_sel_hi:[1,1,0]
	v_pk_fma_f32 v[78:79], v[56:57], v[56:57], v[80:81] op_sel_hi:[1,1,0]
	v_pk_add_f32 v[66:67], v[66:67], v[66:67] op_sel:[0,1] op_sel_hi:[1,0]
	v_pk_add_f32 v[62:63], v[62:63], v[62:63] op_sel:[0,1] op_sel_hi:[1,0]
	v_mov_b32_e32 v77, v53
	v_mov_b32_e32 v79, v85
	v_mov_b32_e32 v67, v91
	v_mov_b32_e32 v63, v90
	v_pk_add_f32 v[64:65], v[76:77], v[78:79]
	v_pk_add_f32 v[62:63], v[62:63], v[66:67]
	s_waitcnt vmcnt(1)
; __device__ __forceinline__ void rms_rows_bf16(const float* srcA, const float* srcB, const float* w, bf16_t* dst, int gw, int NGW, int lane) {
;     ...
;         for (int j = 0; j < 8; ++j) { v[j] = ((const f32x4*)src)[lane + 64 * j]; s += (v[j].x * v[j].x + v[j].y * v[j].y) + (v[j].z * v[j].z + v[j].w * v[j].w); }
;         const float rs = rsqrtf(wave_sum(s) * (1.f / DM) + EPS);
; #pragma unroll
;         for (int j = 0; j < 8; ++j) { const f32x4 wv = ((const f32x4*)w)[lane + 64 * j]; const f32x4 o = v[j] * rs * wv;
;             u32x2 p; p.x = pk2(o.x, o.y); p.y = pk2(o.z, o.w); ((u32x2*)(dst + (size_t)m * DM))[lane + 64 * j] = p; }
	v_mul_f32_e32 v82, v7, v7
	v_mul_f32_e32 v84, v9, v9
	v_pk_add_f32 v[68:69], v[68:69], v[74:75]
	v_pk_add_f32 v[62:63], v[62:63], v[64:65]
	s_waitcnt vmcnt(0)
	v_mul_f32_e32 v88, v4, v4
	v_mul_f32_e32 v89, v5, v5
	v_mul_f32_e32 v92, v2, v2
	v_mul_f32_e32 v93, v3, v3
	v_pk_fma_f32 v[80:81], v[6:7], v[6:7], v[82:83] op_sel_hi:[1,1,0]
	v_pk_fma_f32 v[82:83], v[8:9], v[8:9], v[84:85] op_sel_hi:[1,1,0]
	v_pk_add_f32 v[68:69], v[68:69], v[68:69] op_sel:[0,1] op_sel_hi:[1,0]
	v_pk_add_f32 v[62:63], v[62:63], v[62:63] op_sel:[0,1] op_sel_hi:[1,0]
	v_mov_b32_e32 v81, v88
	v_mov_b32_e32 v83, v89
	v_mov_b32_e32 v69, v93
	v_mov_b32_e32 v63, v92
	v_pk_add_f32 v[70:71], v[80:81], v[82:83]
	v_pk_add_f32 v[62:63], v[62:63], v[68:69]
	s_nop 0
	v_pk_add_f32 v[62:63], v[62:63], v[70:71]
	s_nop 0
	v_add_f32_e32 v53, v62, v63
	ds_bpermute_b32 v62, v1, v53
	s_waitcnt lgkmcnt(0)
	v_add_f32_e32 v53, v53, v62
	ds_bpermute_b32 v62, v42, v53
	s_waitcnt lgkmcnt(0)
	v_add_f32_e32 v53, v53, v62
	ds_bpermute_b32 v62, v43, v53
	s_waitcnt lgkmcnt(0)
	v_add_f32_e32 v53, v53, v62
	ds_bpermute_b32 v62, v44, v53
	s_waitcnt lgkmcnt(0)
	v_add_f32_e32 v53, v53, v62
	ds_bpermute_b32 v62, v45, v53
	s_waitcnt lgkmcnt(0)
	v_add_f32_e32 v53, v53, v62
	ds_bpermute_b32 v62, v46, v53
	s_waitcnt lgkmcnt(0)
	v_add_f32_e32 v53, v53, v62
	v_fmamk_f32 v53, v53, 0x3a000000, v52
	v_mul_f32_e32 v62, 0x4b800000, v53
	v_cmp_gt_f32_e32 vcc, s19, v53
	s_nop 1
	v_cndmask_b32_e32 v53, v53, v62, vcc
	v_rsq_f32_e32 v53, v53
	v_lshl_add_u64 v[62:63], v[40:41], 0, s[14:15]
	v_mul_f32_e32 v64, 0x45800000, v53
	v_cndmask_b32_e32 v64, v53, v64, vcc
	v_pk_mul_f32 v[26:27], v[26:27], v[64:65] op_sel_hi:[1,0]
	v_pk_mul_f32 v[28:29], v[28:29], v[64:65] op_sel_hi:[1,0]
	v_pk_mul_f32 v[26:27], v[100:101], v[26:27]
	v_pk_mul_f32 v[28:29], v[102:103], v[28:29]
	v_add_u32_e32 v26, 0x8000, v26
	v_add_u32_e32 v27, 0x8000, v27
	v_add_u32_e32 v28, 0x8000, v28
	v_add_u32_e32 v29, 0x8000, v29
	v_perm_b32 v26, v27, v26, s22
	v_perm_b32 v27, v29, v28, s22
	global_store_dwordx2 v[62:63], v[26:27], off
	s_nop 1
	v_pk_mul_f32 v[14:15], v[14:15], v[64:65] op_sel_hi:[1,0]
	v_pk_mul_f32 v[16:17], v[16:17], v[64:65] op_sel_hi:[1,0]
	v_pk_mul_f32 v[18:19], v[18:19], v[64:65] op_sel_hi:[1,0]
	v_pk_mul_f32 v[20:21], v[20:21], v[64:65] op_sel_hi:[1,0]
	v_pk_mul_f32 v[10:11], v[10:11], v[64:65] op_sel_hi:[1,0]
	v_pk_mul_f32 v[12:13], v[12:13], v[64:65] op_sel_hi:[1,0]
	v_pk_mul_f32 v[6:7], v[6:7], v[64:65] op_sel_hi:[1,0]
	v_pk_mul_f32 v[8:9], v[8:9], v[64:65] op_sel_hi:[1,0]
	v_pk_mul_f32 v[2:3], v[2:3], v[64:65] op_sel_hi:[1,0]
	v_pk_mul_f32 v[4:5], v[4:5], v[64:65] op_sel_hi:[1,0]
	v_pk_mul_f32 v[16:17], v[106:107], v[16:17]
	v_pk_mul_f32 v[14:15], v[104:105], v[14:15]
	v_add_u32_e32 v16, 0x8000, v16
	v_add_u32_e32 v14, 0x8000, v14
	v_add_u32_e32 v15, 0x8000, v15
	v_add_u32_e32 v17, 0x8000, v17
	v_perm_b32 v14, v15, v14, s22
	v_perm_b32 v15, v17, v16, s22
	global_store_dwordx2 v[62:63], v[14:15], off offset:512
	s_nop 1
	v_pk_mul_f32 v[16:17], v[110:111], v[20:21]
	v_pk_mul_f32 v[14:15], v[108:109], v[18:19]
	v_add_u32_e32 v16, 0x8000, v16
	v_add_u32_e32 v14, 0x8000, v14
	v_add_u32_e32 v15, 0x8000, v15
	v_add_u32_e32 v17, 0x8000, v17
	v_perm_b32 v14, v15, v14, s22
	v_perm_b32 v15, v17, v16, s22
	global_store_dwordx2 v[62:63], v[14:15], off offset:1024
	s_nop 1
	v_pk_mul_f32 v[18:19], v[54:55], v[64:65] op_sel_hi:[1,0]
	v_pk_mul_f32 v[20:21], v[56:57], v[64:65] op_sel_hi:[1,0]
	v_pk_mul_f32 v[14:15], v[112:113], v[18:19]
	v_pk_mul_f32 v[16:17], v[114:115], v[20:21]
	v_add_u32_e32 v14, 0x8000, v14
	v_add_u32_e32 v15, 0x8000, v15
	v_add_u32_e32 v16, 0x8000, v16
	v_add_u32_e32 v17, 0x8000, v17
	v_perm_b32 v14, v15, v14, s22
	v_perm_b32 v15, v17, v16, s22
	global_store_dwordx2 v[62:63], v[14:15], off offset:1536
	s_nop 1
	v_pk_mul_f32 v[18:19], v[22:23], v[64:65] op_sel_hi:[1,0]
	v_pk_mul_f32 v[20:21], v[24:25], v[64:65] op_sel_hi:[1,0]
	v_pk_mul_f32 v[14:15], v[116:117], v[18:19]
	v_pk_mul_f32 v[16:17], v[118:119], v[20:21]
	v_add_u32_e32 v14, 0x8000, v14
	v_add_u32_e32 v15, 0x8000, v15
	v_add_u32_e32 v16, 0x8000, v16
	v_add_u32_e32 v17, 0x8000, v17
	v_perm_b32 v14, v15, v14, s22
	v_perm_b32 v15, v17, v16, s22
	global_store_dwordx2 v[62:63], v[14:15], off offset:2048
	s_nop 1
	v_pk_mul_f32 v[12:13], v[122:123], v[12:13]
	v_pk_mul_f32 v[10:11], v[120:121], v[10:11]
	v_add_u32_e32 v12, 0x8000, v12
	v_add_u32_e32 v10, 0x8000, v10
	v_add_u32_e32 v11, 0x8000, v11
	v_add_u32_e32 v13, 0x8000, v13
	v_perm_b32 v10, v11, v10, s22
	v_perm_b32 v11, v13, v12, s22
	global_store_dwordx2 v[62:63], v[10:11], off offset:2560
	s_nop 1
	v_pk_mul_f32 v[8:9], v[126:127], v[8:9]
	v_pk_mul_f32 v[6:7], v[124:125], v[6:7]
	v_add_u32_e32 v8, 0x8000, v8
	v_add_u32_e32 v6, 0x8000, v6
	v_add_u32_e32 v7, 0x8000, v7
	v_add_u32_e32 v9, 0x8000, v9
	v_perm_b32 v6, v7, v6, s22
	v_perm_b32 v7, v9, v8, s22
	global_store_dwordx2 v[62:63], v[6:7], off offset:3072
	s_nop 1
	v_pk_mul_f32 v[4:5], v[4:5], v[130:131]
	v_pk_mul_f32 v[2:3], v[2:3], v[128:129]
	v_add_u32_e32 v4, 0x8000, v4
	v_add_u32_e32 v2, 0x8000, v2
	v_add_u32_e32 v3, 0x8000, v3
	v_add_u32_e32 v5, 0x8000, v5
	v_perm_b32 v2, v3, v2, s22
	v_perm_b32 v3, v5, v4, s22
	global_store_dwordx2 v[62:63], v[2:3], off offset:3584
	s_cbranch_scc1 .LBB0_48
